# P1 phase_norm0 row loop: all 12 per-row parameter loads issued up front before the next-row x prefetch into dedicated registers, one counted wait instead of a vmcnt(0) per column group
# speedup vs baseline: 1.0102x; 1.0102x over previous
.LBB0_663:
	v_add_u32_e32 v74, s6, v28
	v_min_i32_e32 v56, 0x8000, v28
	v_cmp_gt_i32_e32 vcc, s3, v74
	s_waitcnt vmcnt(0)
	v_pk_mul_f32 v[40:41], v[2:3], v[2:3]
	v_pk_mul_f32 v[42:43], v[6:7], v[6:7]
	v_pk_mul_f32 v[44:45], v[0:1], v[0:1]
	v_pk_mul_f32 v[46:47], v[4:5], v[4:5]
	v_pk_mul_f32 v[48:49], v[14:15], v[14:15]
	v_pk_mul_f32 v[50:51], v[10:11], v[10:11]
	v_pk_mul_f32 v[52:53], v[12:13], v[12:13]
	v_pk_mul_f32 v[54:55], v[8:9], v[8:9]
	v_cndmask_b32_e32 v28, v28, v74, vcc
	v_ashrrev_i32_e32 v60, 12, v56
	v_mov_b32_e32 v56, v52
	v_mov_b32_e32 v57, v54
	v_mov_b32_e32 v54, v53
	v_mov_b32_e32 v52, v48
	v_mov_b32_e32 v53, v50
	v_mov_b32_e32 v50, v49
	v_mov_b32_e32 v48, v44
	v_mov_b32_e32 v49, v46
	v_mov_b32_e32 v46, v45
	v_mov_b32_e32 v44, v40
	v_mov_b32_e32 v45, v42
	v_mov_b32_e32 v42, v41
	v_add_u32_e32 v41, 0xffff8000, v28
	v_mul_i32_i24_e32 v40, 0xc00, v60
	v_cmp_gt_i32_e32 vcc, s14, v28
	v_pk_add_f32 v[46:47], v[48:49], v[46:47]
	global_load_dwordx4 v[36:39], v[18:19], off
	global_load_dwordx4 v[140:143], v[18:19], off offset:1024
	global_load_dwordx4 v[144:147], v[18:19], off offset:2048
	global_load_dwordx4 v[148:151], v[18:19], off offset:3072
	v_cndmask_b32_e32 v48, v41, v28, vcc
	v_ashrrev_i32_e32 v41, 31, v40
	v_lshl_add_u64 v[40:41], v[40:41], 2, s[4:5]
	v_pk_add_f32 v[44:45], v[44:45], v[46:47]
	v_lshl_add_u64 v[66:67], v[40:41], 0, s[12:13]
	v_pk_add_f32 v[64:65], v[42:43], v[44:45]
	v_lshl_add_u64 v[68:69], v[40:41], 0, v[16:17]
	v_lshl_add_u64 v[44:45], v[66:67], 0, v[16:17]
	global_load_dwordx4 v[40:43], v[68:69], off
	global_load_dwordx4 v[152:155], v[68:69], off offset:1024
	global_load_dwordx4 v[156:159], v[68:69], off offset:2048
	global_load_dwordx4 v[160:163], v[68:69], off offset:3072
	s_nop 0
	global_load_dwordx4 v[164:167], v[44:45], off offset:1024
	global_load_dwordx4 v[168:171], v[44:45], off offset:2048
	global_load_dwordx4 v[172:175], v[44:45], off offset:3072
	global_load_dwordx4 v[44:47], v[44:45], off
	v_pk_add_f32 v[54:55], v[56:57], v[54:55]
	v_mov_b32_e32 v25, s57
	v_pk_add_f32 v[52:53], v[52:53], v[54:55]
	v_mov_b32_e32 v27, s53
	v_pk_add_f32 v[50:51], v[50:51], v[52:53]
	v_cndmask_b32_e32 v57, v25, v27, vcc
	v_add_f32_e32 v25, v50, v51
	v_mov_b32_e32 v23, v17
	v_add_f32_e32 v25, v65, v25
	v_lshl_add_u64 v[72:73], v[66:67], 0, v[22:23]
	v_add_f32_e32 v23, v64, v25
	ds_bpermute_b32 v25, v30, v23
	v_mov_b32_e32 v58, s56
	v_mov_b32_e32 v59, s52
	v_ashrrev_i32_e32 v61, 31, v28
	v_cndmask_b32_e32 v49, 0, v61, vcc
	s_waitcnt lgkmcnt(0)
	v_add_f32_e32 v23, v23, v25
	ds_bpermute_b32 v25, v31, v23
	v_cndmask_b32_e32 v56, v58, v59, vcc
	v_lshlrev_b64 v[48:49], 12, v[48:49]
	v_lshl_add_u64 v[48:49], v[56:57], 0, v[48:49]
	v_lshl_add_u64 v[70:71], v[48:49], 0, v[16:17]
	s_waitcnt lgkmcnt(0)
	v_add_f32_e32 v23, v23, v25
	ds_bpermute_b32 v25, v32, v23
	global_load_dwordx4 v[48:51], v[70:71], off
	global_load_dwordx4 v[52:55], v[70:71], off offset:1024
	global_load_dwordx4 v[56:59], v[70:71], off offset:2048
	global_load_dwordx4 v[60:63], v[70:71], off offset:3072
	v_mov_b32_e32 v27, v17
	v_mov_b32_e32 v28, v74
	s_waitcnt lgkmcnt(0)
	v_add_f32_e32 v23, v23, v25
	ds_bpermute_b32 v25, v33, v23
	s_waitcnt lgkmcnt(0)
	v_add_f32_e32 v23, v23, v25
	ds_bpermute_b32 v25, v34, v23
	s_waitcnt lgkmcnt(0)
	v_add_f32_e32 v23, v23, v25
	ds_bpermute_b32 v25, v35, v23
	s_waitcnt lgkmcnt(0)
	v_add_f32_e32 v23, v23, v25
	v_fmamk_f32 v23, v23, 0x3a800000, v29
	v_mul_f32_e32 v25, 0x4b800000, v23
	v_cmp_gt_f32_e32 vcc, s15, v23
	s_nop 1
	v_cndmask_b32_e32 v23, v23, v25, vcc
	v_rsq_f32_e32 v23, v23
	s_nop 0
	v_mul_f32_e32 v25, 0x45800000, v23
	v_cndmask_b32_e32 v64, v23, v25, vcc
	v_pk_mul_f32 v[12:13], v[12:13], v[64:65] op_sel_hi:[1,0]
	v_pk_mul_f32 v[14:15], v[14:15], v[64:65] op_sel_hi:[1,0]
	v_pk_mul_f32 v[8:9], v[8:9], v[64:65] op_sel_hi:[1,0]
	v_pk_mul_f32 v[10:11], v[10:11], v[64:65] op_sel_hi:[1,0]
	v_mov_b32_e32 v25, v17
	v_pk_mul_f32 v[4:5], v[4:5], v[64:65] op_sel_hi:[1,0]
	v_pk_mul_f32 v[6:7], v[6:7], v[64:65] op_sel_hi:[1,0]
	v_cmp_lt_i32_e32 vcc, s7, v74
	s_or_b64 s[10:11], vcc, s[10:11]
	s_waitcnt vmcnt(4)
	v_pk_mul_f32 v[12:13], v[36:37], v[12:13]
	v_pk_mul_f32 v[14:15], v[38:39], v[14:15]
	v_pk_add_f32 v[36:37], v[44:45], 1.0 op_sel_hi:[1,0]
	v_pk_add_f32 v[38:39], v[46:47], 1.0 op_sel_hi:[1,0]
	v_pk_fma_f32 v[12:13], v[36:37], v[12:13], v[40:41]
	v_pk_fma_f32 v[14:15], v[38:39], v[14:15], v[42:43]
	v_cvt_pk_bf16_f32 v12, v12, v13
	v_cvt_pk_bf16_f32 v13, v14, v15
	global_store_dwordx2 v[20:21], v[12:13], off
	s_nop 0
	v_lshl_add_u64 v[44:45], v[66:67], 0, v[24:25]
	v_lshl_add_u64 v[66:67], v[66:67], 0, v[26:27]
	v_pk_mul_f32 v[8:9], v[140:141], v[8:9]
	v_pk_add_f32 v[12:13], v[164:165], 1.0 op_sel_hi:[1, 0]
	v_pk_mul_f32 v[10:11], v[142:143], v[10:11]
	v_pk_add_f32 v[14:15], v[166:167], 1.0 op_sel_hi:[1, 0]
	v_pk_fma_f32 v[8:9], v[12:13], v[8:9], v[152:153]
	v_pk_fma_f32 v[10:11], v[14:15], v[10:11], v[154:155]
	v_cvt_pk_bf16_f32 v8, v8, v9
	v_cvt_pk_bf16_f32 v9, v10, v11
	global_store_dwordx2 v[20:21], v[8:9], off offset:512
	s_nop 0
	v_pk_mul_f32 v[4:5], v[144:145], v[4:5]
	v_pk_add_f32 v[8:9], v[168:169], 1.0 op_sel_hi:[1, 0]
	v_pk_mul_f32 v[6:7], v[146:147], v[6:7]
	v_pk_add_f32 v[10:11], v[170:171], 1.0 op_sel_hi:[1, 0]
	v_pk_fma_f32 v[4:5], v[4:5], v[8:9], v[156:157]
	v_pk_fma_f32 v[6:7], v[6:7], v[10:11], v[158:159]
	v_cvt_pk_bf16_f32 v4, v4, v5
	v_cvt_pk_bf16_f32 v5, v6, v7
	global_store_dwordx2 v[20:21], v[4:5], off offset:1024
	v_pk_mul_f32 v[66:67], v[0:1], v[64:65] op_sel_hi:[1,0]
	v_pk_mul_f32 v[64:65], v[2:3], v[64:65] op_sel_hi:[1,0]
	s_waitcnt vmcnt(3)
	v_mov_b32_e32 v12, v48
	v_mov_b32_e32 v13, v49
	v_mov_b32_e32 v14, v50
	v_mov_b32_e32 v15, v51
	v_mov_b32_e32 v8, v52
	v_mov_b32_e32 v9, v53
	v_mov_b32_e32 v10, v54
	v_mov_b32_e32 v11, v55
	v_mov_b32_e32 v4, v56
	v_mov_b32_e32 v5, v57
	v_mov_b32_e32 v6, v58
	v_mov_b32_e32 v7, v59
	v_mov_b32_e32 v0, v60
	v_mov_b32_e32 v1, v61
	v_mov_b32_e32 v2, v62
	v_mov_b32_e32 v3, v63
	v_pk_mul_f32 v[36:37], v[66:67], v[148:149]
	v_pk_add_f32 v[40:41], v[172:173], 1.0 op_sel_hi:[1, 0]
	v_pk_mul_f32 v[38:39], v[64:65], v[150:151]
	v_pk_add_f32 v[42:43], v[174:175], 1.0 op_sel_hi:[1, 0]
	v_pk_fma_f32 v[36:37], v[36:37], v[40:41], v[160:161]
	v_pk_fma_f32 v[38:39], v[38:39], v[42:43], v[162:163]
	v_cvt_pk_bf16_f32 v36, v36, v37
	v_cvt_pk_bf16_f32 v37, v38, v39
	global_store_dwordx2 v[20:21], v[36:37], off offset:1536
	v_lshl_add_u64 v[20:21], v[20:21], 0, s[8:9]
	s_andn2_b64 exec, exec, s[10:11]
	s_cbranch_execnz .LBB0_663
